# u9 plus: before the serialized out-projection epilogue each wave prefetches its 64 rows x 2 cache lines of the residual stream with two wide loads
# speedup vs baseline: 1.0082x; 1.0082x over previous
; DI int crow(int i, int h) { return (i & 3) + 8 * (i >> 2) + 4 * h; }
; DI const float* xrow(CP p, const Ptrs& w, int l, int tok) {
;   int b = tok / TPB, i = tok - b * TPB;
;   if (l == 0) return i < CTXL ? p.in[2] + (size_t)(b * CTXL + i) * DM : p.in[0] + (size_t)(b * 8192 + i - CTXL) * DM;
;   return i < CTXL ? w.xc1 + (size_t)(b * CTXL + i) * DM : p.out + (size_t)(b * 8192 + i - CTXL) * DM;
; DI void phase_out(CP p, const Ptrs& w, int l, bf16_t* sA, bf16_t* sB) {
;     ...
;         int col = n0 + wn * 64 + ni * 32 + r;
;         float gt = gate[col];
; #pragma unroll
;         for (int i = 0; i < 16; ++i) {
;           int ii = ib + wm * 64 + mi * 32 + crow(i, h);
;           const float* src = xrow(p, w, l, b * TPB + ii);
;           float* dstp = isctx ? w.xc1 + (size_t)(b * CTXL + ii) * DM : p.out + (size_t)(b * 8192 + ii - CTXL) * DM;
;           dstp[col] = src[col] + gt * acc[mi][ni][i];
.LBB0_967:
	s_lshl_b32 s10, s39, 13
	s_addk_i32 s10, 0xff00
	s_lshl_b32 s11, s39, 8
	v_ashrrev_i32_e32 v67, 31, v66
	s_and_b64 s[4:5], s[4:5], exec
	v_lshlrev_b64 v[66:67], 13, v[66:67]
	s_cselect_b32 s39, s11, s10
	v_lshl_add_u64 v[70:71], v[70:71], 0, v[66:67]
	v_add_u32_e32 v66, s39, v72
	v_ashrrev_i32_e32 v67, 31, v66
	s_cselect_b32 s5, s13, s77
	s_cselect_b32 s4, s12, s76
	v_lshlrev_b64 v[66:67], 13, v[66:67]
	v_lshl_add_u64 v[72:73], s[4:5], 0, v[66:67]
	v_lshlrev_b64 v[66:67], 2, v[64:65]
	v_lshl_add_u64 v[70:71], v[70:71], 0, v[66:67]
	s_nop 0
	v_readfirstlane_b32 s100, v70
	v_readfirstlane_b32 s101, v71
	v_mbcnt_lo_u32_b32 v168, -1, 0
	v_mbcnt_hi_u32_b32 v168, -1, v168
	v_lshlrev_b32_e32 v168, 13, v168
	s_nop 2
	global_load_dword v169, v168, s[100:101]
	global_load_dword v169, v168, s[100:101] offset:128
	global_load_dword v74, v[70:71], off
	v_lshl_add_u64 v[70:71], v[72:73], 0, v[66:67]
	v_readlane_b32 s46, v254, 54
	v_readlane_b32 s47, v254, 55
	s_mov_b64 s[10:11], -1
	s_andn2_b64 vcc, exec, s[46:47]
	s_waitcnt vmcnt(0)
	v_fmac_f32_e32 v74, v48, v90
	v_or_b32_e32 v48, v92, v167
	v_add_u32_e32 v72, s38, v48
	v_mul_hi_i32 v73, v72, s0
	global_store_dword v[70:71], v74, off
	v_lshrrev_b32_e32 v74, 31, v73
	v_ashrrev_i32_e32 v73, 11, v73
	v_add_u32_e32 v95, v73, v74
	v_mad_i32_i24 v96, v95, s1, v72
	v_cndmask_b32_e64 v72, 0, 1, s[46:47]
	v_cmp_lt_i32_e64 s[44:45], s37, v96
	v_cmp_ne_u32_e64 s[40:41], 1, v72
	s_cbranch_vccnz .LBB0_973
	s_and_saveexec_b64 s[10:11], s[44:45]
	s_xor_b64 s[10:11], exec, s[10:11]
	v_lshlrev_b32_e32 v72, 13, v95
	s_movk_i32 s46, 0xff00
	v_add3_u32 v72, v72, v96, s46
	s_or_saveexec_b64 s[10:11], s[10:11]
	v_mov_b64_e32 v[74:75], s[76:77]
	s_xor_b64 exec, exec, s[10:11]
	v_lshl_add_u32 v72, v95, 8, v96
	v_mov_b64_e32 v[74:75], s[12:13]
	s_or_b64 exec, exec, s[10:11]
	s_mov_b64 s[10:11], 0
